# first 16 row-sum adds moved between the tile's last PV MFMAs (shorter serial tail)
# speedup vs baseline: 1.0154x; 1.0107x over previous
.Lcj_cx_0:
	v_add_f32_e32 v80, v80, v96
	v_add_f32_e32 v80, v81, v80
	v_add_f32_e32 v80, v82, v80
	v_add_f32_e32 v80, v83, v80
	v_add_f32_e32 v80, v84, v80
	v_add_f32_e32 v80, v85, v80
	v_add_f32_e32 v80, v86, v80
	v_add_f32_e32 v80, v87, v80
	v_add_f32_e32 v80, v88, v80
	v_add_f32_e32 v80, v89, v80
	v_add_f32_e32 v80, v90, v80
	v_add_f32_e32 v80, v91, v80
	v_add_f32_e32 v80, v92, v80
	v_add_f32_e32 v80, v93, v80
	v_add_f32_e32 v80, v94, v80
	v_add_f32_e32 v135, v95, v80
	s_branch .Lcj_common_0
.Lcj_c5_0:
	v_add_f32_e32 v80, v80, v96
	s_waitcnt vmcnt(6)
	v_cvt_pk_bf16_f32 v224, v224, v228
	v_cvt_pk_bf16_f32 v228, v225, v229
	v_cvt_pk_bf16_f32 v225, v232, v236
	v_add_f32_e32 v80, v81, v80
	v_cvt_pk_bf16_f32 v232, v226, v230
	v_cvt_pk_bf16_f32 v226, v240, v244
	v_cvt_pk_bf16_f32 v236, v227, v231
	v_cvt_pk_bf16_f32 v227, v248, v252
	v_add_f32_e32 v80, v82, v80
	v_cvt_pk_bf16_f32 v229, v233, v237
	v_cvt_pk_bf16_f32 v230, v241, v245
	v_cvt_pk_bf16_f32 v231, v249, v253
	v_cvt_pk_bf16_f32 v233, v234, v238
	v_add_f32_e32 v80, v83, v80
	v_cvt_pk_bf16_f32 v234, v242, v246
	v_cvt_pk_bf16_f32 v237, v235, v239
	v_cvt_pk_bf16_f32 v235, v250, v254
	v_cvt_pk_bf16_f32 v238, v243, v247
	v_add_f32_e32 v80, v84, v80
	v_cvt_pk_bf16_f32 v239, v251, v255
	s_lshr_b32 s91, s2, 7
	s_lshl_b32 s92, s98, 1
	s_add_i32 s91, s91, s92
	v_add_f32_e32 v80, v85, v80
	s_mul_i32 s92, s91, 0xab
	s_lshr_b32 s92, s92, 9
	s_mul_i32 s93, s92, 3
	s_sub_i32 s91, s91, s93
	v_add_f32_e32 v80, v86, v80
	v_mbcnt_lo_u32_b32 v222, -1, 0
	v_mbcnt_hi_u32_b32 v222, -1, v222
	s_and_b32 s93, s2, 0x7f
	s_lshl_b32 s93, s93, 9
	v_add_f32_e32 v80, v87, v80
	s_or_b32 s93, s93, s63
	v_or_b32_e32 v222, s93, v222
	s_cmp_eq_u32 s91, 2
	s_cselect_b32 s93, 12, 11
	v_add_f32_e32 v80, v88, v80
	v_lshrrev_b32_e32 v223, s93, v222
	v_and_b32_e32 v208, 7, v222
	v_lshl_or_b32 v223, v223, 3, v208
	s_cselect_b32 s93, 6, 5
	v_add_f32_e32 v80, v89, v80
	v_bfe_u32 v208, v222, 6, s93
	v_lshrrev_b32_e32 v222, 1, v222
	v_and_b32_e32 v222, 28, v222
	v_lshl_or_b32 v222, v208, 5, v222
	v_add_f32_e32 v80, v90, v80
	s_cselect_b64 vcc, exec, 0
	s_cselect_b32 s94, 11, 12
	s_cselect_b64 s[100:101], s[86:87], s[84:85]
	s_cselect_b32 s93, 22, 23
	v_add_f32_e32 v80, v91, v80
	v_lshrrev_b32_e32 v208, 7, v222
	v_and_b32_e32 v240, 0x7f, v222
	s_lshl_b32 s92, s92, s93
	v_lshl_or_b32 v208, v208, 8, v240
	v_add_f32_e32 v80, v92, v80
	s_lshl_b32 s93, s91, 7
	v_or_b32_e32 v208, s93, v208
	v_cndmask_b32_e32 v222, v208, v222, vcc
	v_lshlrev_b32_e32 v222, s94, v222
	v_add_f32_e32 v80, v93, v80
	s_lshl_b32 s94, 1, s94
	v_lshl_or_b32 v222, v223, 4, v222
	s_add_u32 s100, s100, s92
	s_addc_u32 s101, s101, 0
	v_add_f32_e32 v80, v94, v80
	s_mov_b32 s95, 5
	v_add_f32_e32 v135, v95, v80
	s_branch .Lcj_common_0
.Lcj_c7_0:
	v_add_f32_e32 v80, v80, v96
	s_add_i32 s98, s98, 1
	s_min_u32 s98, s98, 47
	s_lshr_b32 s91, s2, 7
	v_add_f32_e32 v80, v81, v80
	s_lshl_b32 s92, s98, 1
	s_add_i32 s91, s91, s92
	s_mul_i32 s92, s91, 0xab
	v_add_f32_e32 v80, v82, v80
	s_lshr_b32 s92, s92, 9
	s_mul_i32 s93, s92, 3
	s_sub_i32 s91, s91, s93
	v_add_f32_e32 v80, v83, v80
	v_mbcnt_lo_u32_b32 v222, -1, 0
	v_mbcnt_hi_u32_b32 v222, -1, v222
	s_and_b32 s93, s2, 0x7f
	v_add_f32_e32 v80, v84, v80
	s_lshl_b32 s93, s93, 9
	s_or_b32 s93, s93, s63
	v_or_b32_e32 v222, s93, v222
	v_add_f32_e32 v80, v85, v80
	s_cmp_eq_u32 s91, 2
	s_cselect_b32 s93, 12, 11
	v_lshrrev_b32_e32 v223, s93, v222
	v_add_f32_e32 v80, v86, v80
	v_and_b32_e32 v208, 7, v222
	v_lshl_or_b32 v223, v223, 3, v208
	s_cselect_b32 s93, 6, 5
	v_add_f32_e32 v80, v87, v80
	v_bfe_u32 v208, v222, 6, s93
	v_lshrrev_b32_e32 v222, 1, v222
	v_and_b32_e32 v222, 28, v222
	v_add_f32_e32 v80, v88, v80
	v_lshl_or_b32 v222, v208, 5, v222
	v_lshlrev_b32_e32 v222, 2, v222
	s_cselect_b32 s93, 16, 15
	v_add_f32_e32 v80, v89, v80
	v_lshlrev_b32_e32 v223, s93, v223
	v_add_u32_e32 v222, v223, v222
	s_cselect_b32 s94, 1, 0
	v_add_f32_e32 v80, v90, v80
	s_lshl_b32 s94, 0x1000, s94
	s_lshl_b32 s92, s92, 23
	s_cmp_eq_u32 s91, 0
	v_add_f32_e32 v80, v91, v80
	s_cselect_b64 s[100:101], s[76:77], s[78:79]
	s_cmp_eq_u32 s91, 2
	s_cselect_b64 s[100:101], s[80:81], s[100:101]
	v_add_f32_e32 v80, v92, v80
	s_add_u32 s100, s100, s92
	s_addc_u32 s101, s101, 0
	s_mov_b32 s95, 1
	v_add_f32_e32 v80, v93, v80
	s_cmp_lt_u32 s4, 56
	s_cselect_b32 s95, 1, 0
	v_add_f32_e32 v80, v94, v80
	v_add_f32_e32 v135, v95, v80

.Lcjh_done_0:
	ds_read_b128 v[80:83], v85 offset:2048
	ds_read_b128 v[188:191], v85 offset:2560
	v_add3_u32 v85, s34, v180, v176
	s_mov_b64 s[34:35], -1
	ds_read_b128 v[192:195], v84 offset:4608
	s_waitcnt lgkmcnt(0)
	v_mfma_f32_32x32x16_bf16 v[96:111], v[80:83], v[116:119], v[96:111]
	ds_read_b128 v[80:83], v84 offset:4096
	s_waitcnt lgkmcnt(0)
	v_mfma_f32_32x32x16_bf16 v[96:111], v[80:83], v[120:123], v[96:111]
	ds_read_b128 v[80:83], v85 offset:6144
	ds_read_b128 v[196:199], v85 offset:6656
	s_waitcnt lgkmcnt(0)
	v_mfma_f32_32x32x16_bf16 v[96:111], v[80:83], v[124:127], v[96:111]
	v_mfma_f32_32x32x16_bf16 v[80:95], v[184:187], v[112:115], v[0:15]
	ds_read_b128 v[184:187], v200 offset:16384
	s_nop 9
	v_exp_f32_e32 v96, v96
	v_exp_f32_e32 v97, v97
	v_exp_f32_e32 v98, v98
	v_exp_f32_e32 v99, v99
	v_exp_f32_e32 v100, v100
	v_exp_f32_e32 v101, v101
	v_mfma_f32_32x32x16_bf16 v[80:95], v[188:191], v[116:119], v[80:95]
	v_exp_f32_e32 v102, v102
	v_exp_f32_e32 v103, v103
	v_cvt_pk_bf16_f32 v188, v96, v97
	v_cvt_pk_bf16_f32 v189, v98, v99
	v_cvt_pk_bf16_f32 v190, v100, v101
	v_cvt_pk_bf16_f32 v191, v102, v103
	v_exp_f32_e32 v104, v104
	v_mfma_f32_32x32x16_bf16 v[80:95], v[192:195], v[120:123], v[80:95]
	ds_read_b128 v[192:195], v200 offset:17408
	v_exp_f32_e32 v105, v105
	v_exp_f32_e32 v106, v106
	v_exp_f32_e32 v107, v107
	v_exp_f32_e32 v108, v108
	v_exp_f32_e32 v109, v109
	v_exp_f32_e32 v110, v110
	v_mfma_f32_32x32x16_bf16 v[80:95], v[196:199], v[124:127], v[80:95]
	v_exp_f32_e32 v111, v111
	s_waitcnt lgkmcnt(0)
	v_mfma_f32_32x32x16_bf16 v[64:79], v[184:187], v[188:191], v[64:79]
	ds_read_b128 v[184:187], v201 offset:16896
	ds_read_b128 v[196:199], v201 offset:17920
	s_nop 6
	v_exp_f32_e32 v80, v80
	v_exp_f32_e32 v81, v81
	v_exp_f32_e32 v82, v82
	v_exp_f32_e32 v83, v83
	v_exp_f32_e32 v84, v84
	v_exp_f32_e32 v85, v85
	s_waitcnt lgkmcnt(0)
	v_mfma_f32_32x32x16_bf16 v[48:63], v[184:187], v[188:191], v[48:63]
	ds_read_b128 v[184:187], v200 offset:20480
	v_exp_f32_e32 v86, v86
	v_exp_f32_e32 v87, v87
	v_exp_f32_e32 v88, v88
	v_exp_f32_e32 v89, v89
	v_exp_f32_e32 v90, v90
	v_exp_f32_e32 v91, v91
	v_mfma_f32_32x32x16_bf16 v[32:47], v[192:195], v[188:191], v[32:47]
	ds_read_b128 v[192:195], v200 offset:21504
	v_exp_f32_e32 v92, v92
	v_exp_f32_e32 v93, v93
	v_exp_f32_e32 v94, v94
	v_exp_f32_e32 v95, v95
	v_mfma_f32_32x32x16_bf16 v[16:31], v[196:199], v[188:191], v[16:31]
	v_cvt_pk_bf16_f32 v188, v104, v105
	v_cvt_pk_bf16_f32 v189, v106, v107
	v_cvt_pk_bf16_f32 v190, v108, v109
	v_cvt_pk_bf16_f32 v191, v110, v111
	s_waitcnt lgkmcnt(0)
	s_nop 0
	v_mfma_f32_32x32x16_bf16 v[64:79], v[184:187], v[188:191], v[64:79]
	ds_read_b128 v[184:187], v201 offset:20992
	ds_read_b128 v[196:199], v201 offset:22016
	s_waitcnt lgkmcnt(0)
	v_mfma_f32_32x32x16_bf16 v[48:63], v[184:187], v[188:191], v[48:63]
	ds_read_b128 v[184:187], v200 offset:24576
	v_mfma_f32_32x32x16_bf16 v[32:47], v[192:195], v[188:191], v[32:47]
	ds_read_b128 v[192:195], v200 offset:25600
	v_mfma_f32_32x32x16_bf16 v[16:31], v[196:199], v[188:191], v[16:31]
	v_cvt_pk_bf16_f32 v188, v80, v81
	v_cvt_pk_bf16_f32 v189, v82, v83
	v_cvt_pk_bf16_f32 v190, v84, v85
	v_cvt_pk_bf16_f32 v191, v86, v87
	s_waitcnt lgkmcnt(0)
	s_nop 0
	v_mfma_f32_32x32x16_bf16 v[64:79], v[184:187], v[188:191], v[64:79]
	ds_read_b128 v[184:187], v201 offset:25088
	ds_read_b128 v[196:199], v201 offset:26112
	s_waitcnt lgkmcnt(0)
	v_mfma_f32_32x32x16_bf16 v[48:63], v[184:187], v[188:191], v[48:63]
	ds_read_b128 v[184:187], v200 offset:28672
	v_mfma_f32_32x32x16_bf16 v[32:47], v[192:195], v[188:191], v[32:47]
	ds_read_b128 v[192:195], v200 offset:29696
	v_mfma_f32_32x32x16_bf16 v[16:31], v[196:199], v[188:191], v[16:31]
	v_cvt_pk_bf16_f32 v188, v88, v89
	v_cvt_pk_bf16_f32 v189, v90, v91
	v_cvt_pk_bf16_f32 v190, v92, v93
	v_cvt_pk_bf16_f32 v191, v94, v95
	s_waitcnt lgkmcnt(0)
	s_nop 0
	v_mfma_f32_32x32x16_bf16 v[64:79], v[184:187], v[188:191], v[64:79]
	ds_read_b128 v[184:187], v201 offset:29184
	ds_read_b128 v[196:199], v201 offset:30208
	s_waitcnt lgkmcnt(0)
	v_mfma_f32_32x32x16_bf16 v[48:63], v[184:187], v[188:191], v[48:63]
	v_add_f32_e32 v96, v135, v96
	v_add_f32_e32 v96, v97, v96
	v_add_f32_e32 v96, v98, v96
	v_add_f32_e32 v96, v99, v96
	v_add_f32_e32 v96, v100, v96
	v_add_f32_e32 v96, v101, v96
	v_add_f32_e32 v96, v102, v96
	v_add_f32_e32 v96, v103, v96
	v_mfma_f32_32x32x16_bf16 v[32:47], v[192:195], v[188:191], v[32:47]
	v_add_f32_e32 v96, v104, v96
	v_add_f32_e32 v96, v105, v96
	v_add_f32_e32 v96, v106, v96
	v_add_f32_e32 v96, v107, v96
	v_add_f32_e32 v96, v108, v96
	v_add_f32_e32 v96, v109, v96
	v_add_f32_e32 v96, v110, v96
	v_add_f32_e32 v96, v111, v96
	v_mfma_f32_32x32x16_bf16 v[16:31], v[196:199], v[188:191], v[16:31]
	s_cbranch_vccz .Lcj_cnt_0
	s_waitcnt vmcnt(0)
	s_branch .LBB0_1448

.Lcjh_done_1:
	ds_read_b128 v[80:83], v85 offset:2048
	ds_read_b128 v[156:159], v85 offset:2560
	v_add3_u32 v85, s18, v180, v176
	s_mov_b64 s[18:19], -1
	ds_read_b128 v[160:163], v84 offset:4608
	s_waitcnt lgkmcnt(0)
	v_mfma_f32_32x32x16_bf16 v[96:111], v[80:83], v[116:119], v[96:111]
	ds_read_b128 v[80:83], v84 offset:4096
	s_waitcnt lgkmcnt(0)
	v_mfma_f32_32x32x16_bf16 v[96:111], v[80:83], v[120:123], v[96:111]
	ds_read_b128 v[80:83], v85 offset:6144
	ds_read_b128 v[218:221], v85 offset:6656
	s_waitcnt lgkmcnt(0)
	v_mfma_f32_32x32x16_bf16 v[96:111], v[80:83], v[124:127], v[96:111]
	v_mfma_f32_32x32x16_bf16 v[80:95], v[152:155], v[112:115], v[0:15]
	ds_read_b128 v[152:155], v209 offset:16384
	s_nop 9
	v_exp_f32_e32 v96, v96
	v_exp_f32_e32 v97, v97
	v_exp_f32_e32 v98, v98
	v_exp_f32_e32 v99, v99
	v_exp_f32_e32 v100, v100
	v_exp_f32_e32 v101, v101
	v_mfma_f32_32x32x16_bf16 v[80:95], v[156:159], v[116:119], v[80:95]
	v_exp_f32_e32 v102, v102
	v_exp_f32_e32 v103, v103
	v_cvt_pk_bf16_f32 v156, v96, v97
	v_cvt_pk_bf16_f32 v157, v98, v99
	v_cvt_pk_bf16_f32 v158, v100, v101
	v_cvt_pk_bf16_f32 v159, v102, v103
	v_exp_f32_e32 v104, v104
	v_mfma_f32_32x32x16_bf16 v[80:95], v[160:163], v[120:123], v[80:95]
	ds_read_b128 v[160:163], v209 offset:17408
	v_exp_f32_e32 v105, v105
	v_exp_f32_e32 v106, v106
	v_exp_f32_e32 v107, v107
	v_exp_f32_e32 v108, v108
	v_exp_f32_e32 v109, v109
	v_exp_f32_e32 v110, v110
	v_mfma_f32_32x32x16_bf16 v[80:95], v[218:221], v[124:127], v[80:95]
	v_exp_f32_e32 v111, v111
	s_waitcnt lgkmcnt(0)
	v_mfma_f32_32x32x16_bf16 v[64:79], v[152:155], v[156:159], v[64:79]
	ds_read_b128 v[152:155], v211 offset:16896
	ds_read_b128 v[218:221], v211 offset:17920
	s_nop 6
	v_exp_f32_e32 v80, v80
	v_exp_f32_e32 v81, v81
	v_exp_f32_e32 v82, v82
	v_exp_f32_e32 v83, v83
	v_exp_f32_e32 v84, v84
	v_exp_f32_e32 v85, v85
	s_waitcnt lgkmcnt(0)
	v_mfma_f32_32x32x16_bf16 v[48:63], v[152:155], v[156:159], v[48:63]
	ds_read_b128 v[152:155], v209 offset:20480
	v_exp_f32_e32 v86, v86
	v_exp_f32_e32 v87, v87
	v_exp_f32_e32 v88, v88
	v_exp_f32_e32 v89, v89
	v_exp_f32_e32 v90, v90
	v_exp_f32_e32 v91, v91
	v_mfma_f32_32x32x16_bf16 v[32:47], v[160:163], v[156:159], v[32:47]
	ds_read_b128 v[160:163], v209 offset:21504
	v_exp_f32_e32 v92, v92
	v_exp_f32_e32 v93, v93
	v_exp_f32_e32 v94, v94
	v_exp_f32_e32 v95, v95
	v_mfma_f32_32x32x16_bf16 v[16:31], v[218:221], v[156:159], v[16:31]
	v_cvt_pk_bf16_f32 v156, v104, v105
	v_cvt_pk_bf16_f32 v157, v106, v107
	v_cvt_pk_bf16_f32 v158, v108, v109
	v_cvt_pk_bf16_f32 v159, v110, v111
	s_waitcnt lgkmcnt(0)
	s_nop 0
	v_mfma_f32_32x32x16_bf16 v[64:79], v[152:155], v[156:159], v[64:79]
	ds_read_b128 v[152:155], v211 offset:20992
	ds_read_b128 v[218:221], v211 offset:22016
	s_waitcnt lgkmcnt(0)
	v_mfma_f32_32x32x16_bf16 v[48:63], v[152:155], v[156:159], v[48:63]
	ds_read_b128 v[152:155], v209 offset:24576
	v_mfma_f32_32x32x16_bf16 v[32:47], v[160:163], v[156:159], v[32:47]
	ds_read_b128 v[160:163], v209 offset:25600
	v_mfma_f32_32x32x16_bf16 v[16:31], v[218:221], v[156:159], v[16:31]
	v_cvt_pk_bf16_f32 v156, v80, v81
	v_cvt_pk_bf16_f32 v157, v82, v83
	v_cvt_pk_bf16_f32 v158, v84, v85
	v_cvt_pk_bf16_f32 v159, v86, v87
	s_waitcnt lgkmcnt(0)
	s_nop 0
	v_mfma_f32_32x32x16_bf16 v[64:79], v[152:155], v[156:159], v[64:79]
	ds_read_b128 v[152:155], v211 offset:25088
	ds_read_b128 v[218:221], v211 offset:26112
	s_waitcnt lgkmcnt(0)
	v_mfma_f32_32x32x16_bf16 v[48:63], v[152:155], v[156:159], v[48:63]
	ds_read_b128 v[152:155], v209 offset:28672
	v_mfma_f32_32x32x16_bf16 v[32:47], v[160:163], v[156:159], v[32:47]
	ds_read_b128 v[160:163], v209 offset:29696
	v_mfma_f32_32x32x16_bf16 v[16:31], v[218:221], v[156:159], v[16:31]
	v_cvt_pk_bf16_f32 v156, v88, v89
	v_cvt_pk_bf16_f32 v157, v90, v91
	v_cvt_pk_bf16_f32 v158, v92, v93
	v_cvt_pk_bf16_f32 v159, v94, v95
	s_waitcnt lgkmcnt(0)
	s_nop 0
	v_mfma_f32_32x32x16_bf16 v[64:79], v[152:155], v[156:159], v[64:79]
	ds_read_b128 v[152:155], v211 offset:29184
	ds_read_b128 v[218:221], v211 offset:30208
	s_waitcnt lgkmcnt(0)
	v_mfma_f32_32x32x16_bf16 v[48:63], v[152:155], v[156:159], v[48:63]
	v_add_f32_e32 v96, v135, v96
	v_add_f32_e32 v96, v97, v96
	v_add_f32_e32 v96, v98, v96
	v_add_f32_e32 v96, v99, v96
	v_add_f32_e32 v96, v100, v96
	v_add_f32_e32 v96, v101, v96
	v_add_f32_e32 v96, v102, v96
	v_add_f32_e32 v96, v103, v96
	v_mfma_f32_32x32x16_bf16 v[32:47], v[160:163], v[156:159], v[32:47]
	v_add_f32_e32 v96, v104, v96
	v_add_f32_e32 v96, v105, v96
	v_add_f32_e32 v96, v106, v96
	v_add_f32_e32 v96, v107, v96
	v_add_f32_e32 v96, v108, v96
	v_add_f32_e32 v96, v109, v96
	v_add_f32_e32 v96, v110, v96
	v_add_f32_e32 v96, v111, v96
	v_mfma_f32_32x32x16_bf16 v[16:31], v[218:221], v[156:159], v[16:31]
	s_cbranch_vccz .Lcj_cnt_1
	s_waitcnt vmcnt(0)
	s_branch .LBB0_1456
